# tile headers: store-drain wait sunk below the accumulator zeroing and hoisted address math (overlaps zeroing with the drain)
# baseline (speedup 1.0000x reference)
.LBB0_146:
	s_ashr_i32 s11, s10, 31
	v_cmp_lt_i64_e32 vcc, s[12:13], v[140:141]
	s_lshl_b64 s[12:13], s[10:11], 20
	s_add_u32 s12, s80, s12
	s_addc_u32 s13, s81, s13
	s_and_b64 s[14:15], vcc, exec
	s_cselect_b32 s11, s13, s17
	s_cselect_b32 s41, s12, s16
	s_ashr_i32 s9, s8, 31
	s_lshl_b64 s[14:15], s[8:9], 20
	s_add_u32 s14, s22, s14
	s_addc_u32 s15, s23, s15
	s_and_b64 s[20:21], vcc, exec
	s_cselect_b32 s9, s15, s19
	s_cselect_b32 s44, s14, s18
	s_add_u32 s16, s16, 0x80080
	s_addc_u32 s17, s17, 0
	s_add_u32 s45, s18, 0x100
	v_mov_b32_e32 v0, 0
	s_addc_u32 s46, s19, 0
	s_mov_b32 s47, -2
	v_mov_b32_e32 v1, v0
	v_mov_b32_e32 v2, v0
	v_mov_b32_e32 v3, v0
	v_mov_b32_e32 v4, v0
	v_mov_b32_e32 v5, v0
	v_mov_b32_e32 v6, v0
	v_mov_b32_e32 v7, v0
	v_mov_b32_e32 v16, v0
	v_mov_b32_e32 v17, v0
	v_mov_b32_e32 v18, v0
	v_mov_b32_e32 v19, v0
	v_mov_b32_e32 v20, v0
	v_mov_b32_e32 v21, v0
	v_mov_b32_e32 v22, v0
	v_mov_b32_e32 v23, v0
	v_mov_b32_e32 v32, v0
	v_mov_b32_e32 v33, v0
	v_mov_b32_e32 v34, v0
	v_mov_b32_e32 v35, v0
	v_mov_b32_e32 v36, v0
	v_mov_b32_e32 v37, v0
	v_mov_b32_e32 v38, v0
	v_mov_b32_e32 v39, v0
	v_mov_b32_e32 v48, v0
	v_mov_b32_e32 v49, v0
	v_mov_b32_e32 v50, v0
	v_mov_b32_e32 v51, v0
	v_mov_b32_e32 v52, v0
	v_mov_b32_e32 v53, v0
	v_mov_b32_e32 v54, v0
	v_mov_b32_e32 v55, v0
	v_mov_b32_e32 v8, v0
	v_mov_b32_e32 v9, v0
	v_mov_b32_e32 v10, v0
	v_mov_b32_e32 v11, v0
	v_mov_b32_e32 v12, v0
	v_mov_b32_e32 v13, v0
	v_mov_b32_e32 v14, v0
	v_mov_b32_e32 v15, v0
	v_mov_b32_e32 v24, v0
	v_mov_b32_e32 v25, v0
	v_mov_b32_e32 v26, v0
	v_mov_b32_e32 v27, v0
	v_mov_b32_e32 v28, v0
	v_mov_b32_e32 v29, v0
	v_mov_b32_e32 v30, v0
	v_mov_b32_e32 v31, v0
	v_mov_b32_e32 v40, v0
	v_mov_b32_e32 v41, v0
	v_mov_b32_e32 v42, v0
	v_mov_b32_e32 v43, v0
	v_mov_b32_e32 v44, v0
	v_mov_b32_e32 v45, v0
	v_mov_b32_e32 v46, v0
	v_mov_b32_e32 v47, v0
	v_mov_b32_e32 v56, v0
	v_mov_b32_e32 v57, v0
	v_mov_b32_e32 v58, v0
	v_mov_b32_e32 v59, v0
	v_mov_b32_e32 v60, v0
	v_mov_b32_e32 v61, v0
	v_mov_b32_e32 v62, v0
	v_mov_b32_e32 v63, v0
	v_mov_b32_e32 v64, v0
	v_mov_b32_e32 v65, v0
	v_mov_b32_e32 v66, v0
	v_mov_b32_e32 v67, v0
	v_mov_b32_e32 v68, v0
	v_mov_b32_e32 v69, v0
	v_mov_b32_e32 v70, v0
	v_mov_b32_e32 v71, v0
	v_mov_b32_e32 v80, v0
	v_mov_b32_e32 v81, v0
	v_mov_b32_e32 v82, v0
	v_mov_b32_e32 v83, v0
	v_mov_b32_e32 v84, v0
	v_mov_b32_e32 v85, v0
	v_mov_b32_e32 v86, v0
	v_mov_b32_e32 v87, v0
	v_mov_b32_e32 v96, v0
	v_mov_b32_e32 v97, v0
	v_mov_b32_e32 v98, v0
	v_mov_b32_e32 v99, v0
	v_mov_b32_e32 v100, v0
	v_mov_b32_e32 v101, v0
	v_mov_b32_e32 v102, v0
	v_mov_b32_e32 v103, v0
	v_mov_b32_e32 v112, v0
	v_mov_b32_e32 v113, v0
	v_mov_b32_e32 v114, v0
	v_mov_b32_e32 v115, v0
	v_mov_b32_e32 v116, v0
	v_mov_b32_e32 v117, v0
	v_mov_b32_e32 v118, v0
	v_mov_b32_e32 v119, v0
	v_mov_b32_e32 v72, v0
	v_mov_b32_e32 v73, v0
	v_mov_b32_e32 v74, v0
	v_mov_b32_e32 v75, v0
	v_mov_b32_e32 v76, v0
	v_mov_b32_e32 v77, v0
	v_mov_b32_e32 v78, v0
	v_mov_b32_e32 v79, v0
	v_mov_b32_e32 v88, v0
	v_mov_b32_e32 v89, v0
	v_mov_b32_e32 v90, v0
	v_mov_b32_e32 v91, v0
	v_mov_b32_e32 v92, v0
	v_mov_b32_e32 v93, v0
	v_mov_b32_e32 v94, v0
	v_mov_b32_e32 v95, v0
	v_mov_b32_e32 v104, v0
	v_mov_b32_e32 v105, v0
	v_mov_b32_e32 v106, v0
	v_mov_b32_e32 v107, v0
	v_mov_b32_e32 v108, v0
	v_mov_b32_e32 v109, v0
	v_mov_b32_e32 v110, v0
	v_mov_b32_e32 v111, v0
	v_mov_b32_e32 v120, v0
	v_mov_b32_e32 v121, v0
	v_mov_b32_e32 v122, v0
	v_mov_b32_e32 v123, v0
	v_mov_b32_e32 v124, v0
	v_mov_b32_e32 v125, v0
	v_mov_b32_e32 v126, v0
	v_mov_b32_e32 v127, v0
	v_xor_b32_e32 v220, 64, v165
	v_xor_b32_e32 v221, 64, v166
	v_xor_b32_e32 v234, 64, v167
	v_add_u32_e32 v235, 0x18000, v161
	v_xor_b32_e32 v236, 64, v235
	s_waitcnt vmcnt(0)
	s_cmpk_lt_u32 s3, 0x100
	s_cbranch_scc1 .Lst_in_s1
	s_barrier

.LBB0_282:
	s_ashr_i32 s11, s10, 31
	s_lshl_b64 s[16:17], s[10:11], 20
	s_add_u32 s16, s22, s16
	s_addc_u32 s17, s23, s17
	s_and_b64 s[6:7], s[6:7], exec
	s_cselect_b32 s1, s17, s19
	s_cselect_b32 s11, s16, s18
	s_add_u32 s6, s20, 0x180080
	s_addc_u32 s7, s21, 0
	s_add_u32 s43, s18, 0x100
	v_mov_b32_e32 v0, 0
	s_addc_u32 s44, s19, 0
	s_mov_b32 s45, -2
	s_waitcnt lgkmcnt(0)
	v_mov_b32_e32 v1, v0
	v_mov_b32_e32 v2, v0
	v_mov_b32_e32 v3, v0
	v_mov_b32_e32 v4, v0
	v_mov_b32_e32 v5, v0
	v_mov_b32_e32 v6, v0
	v_mov_b32_e32 v7, v0
	v_mov_b32_e32 v16, v0
	v_mov_b32_e32 v17, v0
	v_mov_b32_e32 v18, v0
	v_mov_b32_e32 v19, v0
	v_mov_b32_e32 v20, v0
	v_mov_b32_e32 v21, v0
	v_mov_b32_e32 v22, v0
	v_mov_b32_e32 v23, v0
	v_mov_b32_e32 v32, v0
	v_mov_b32_e32 v33, v0
	v_mov_b32_e32 v34, v0
	v_mov_b32_e32 v35, v0
	v_mov_b32_e32 v36, v0
	v_mov_b32_e32 v37, v0
	v_mov_b32_e32 v38, v0
	v_mov_b32_e32 v39, v0
	v_mov_b32_e32 v48, v0
	v_mov_b32_e32 v49, v0
	v_mov_b32_e32 v50, v0
	v_mov_b32_e32 v51, v0
	v_mov_b32_e32 v52, v0
	v_mov_b32_e32 v53, v0
	v_mov_b32_e32 v54, v0
	v_mov_b32_e32 v55, v0
	v_mov_b32_e32 v8, v0
	v_mov_b32_e32 v9, v0
	v_mov_b32_e32 v10, v0
	v_mov_b32_e32 v11, v0
	v_mov_b32_e32 v12, v0
	v_mov_b32_e32 v13, v0
	v_mov_b32_e32 v14, v0
	v_mov_b32_e32 v15, v0
	v_mov_b32_e32 v24, v0
	v_mov_b32_e32 v25, v0
	v_mov_b32_e32 v26, v0
	v_mov_b32_e32 v27, v0
	v_mov_b32_e32 v28, v0
	v_mov_b32_e32 v29, v0
	v_mov_b32_e32 v30, v0
	v_mov_b32_e32 v31, v0
	v_mov_b32_e32 v40, v0
	v_mov_b32_e32 v41, v0
	v_mov_b32_e32 v42, v0
	v_mov_b32_e32 v43, v0
	v_mov_b32_e32 v44, v0
	v_mov_b32_e32 v45, v0
	v_mov_b32_e32 v46, v0
	v_mov_b32_e32 v47, v0
	v_mov_b32_e32 v56, v0
	v_mov_b32_e32 v57, v0
	v_mov_b32_e32 v58, v0
	v_mov_b32_e32 v59, v0
	v_mov_b32_e32 v60, v0
	v_mov_b32_e32 v61, v0
	v_mov_b32_e32 v62, v0
	v_mov_b32_e32 v63, v0
	v_mov_b32_e32 v64, v0
	v_mov_b32_e32 v65, v0
	v_mov_b32_e32 v66, v0
	v_mov_b32_e32 v67, v0
	v_mov_b32_e32 v68, v0
	v_mov_b32_e32 v69, v0
	v_mov_b32_e32 v70, v0
	v_mov_b32_e32 v71, v0
	v_mov_b32_e32 v80, v0
	v_mov_b32_e32 v81, v0
	v_mov_b32_e32 v82, v0
	v_mov_b32_e32 v83, v0
	v_mov_b32_e32 v84, v0
	v_mov_b32_e32 v85, v0
	v_mov_b32_e32 v86, v0
	v_mov_b32_e32 v87, v0
	v_mov_b32_e32 v96, v0
	v_mov_b32_e32 v97, v0
	v_mov_b32_e32 v98, v0
	v_mov_b32_e32 v99, v0
	v_mov_b32_e32 v100, v0
	v_mov_b32_e32 v101, v0
	v_mov_b32_e32 v102, v0
	v_mov_b32_e32 v103, v0
	v_mov_b32_e32 v112, v0
	v_mov_b32_e32 v113, v0
	v_mov_b32_e32 v114, v0
	v_mov_b32_e32 v115, v0
	v_mov_b32_e32 v116, v0
	v_mov_b32_e32 v117, v0
	v_mov_b32_e32 v118, v0
	v_mov_b32_e32 v119, v0
	v_mov_b32_e32 v72, v0
	v_mov_b32_e32 v73, v0
	v_mov_b32_e32 v74, v0
	v_mov_b32_e32 v75, v0
	v_mov_b32_e32 v76, v0
	v_mov_b32_e32 v77, v0
	v_mov_b32_e32 v78, v0
	v_mov_b32_e32 v79, v0
	v_mov_b32_e32 v88, v0
	v_mov_b32_e32 v89, v0
	v_mov_b32_e32 v90, v0
	v_mov_b32_e32 v91, v0
	v_mov_b32_e32 v92, v0
	v_mov_b32_e32 v93, v0
	v_mov_b32_e32 v94, v0
	v_mov_b32_e32 v95, v0
	v_mov_b32_e32 v104, v0
	v_mov_b32_e32 v105, v0
	v_mov_b32_e32 v106, v0
	v_mov_b32_e32 v107, v0
	v_mov_b32_e32 v108, v0
	v_mov_b32_e32 v109, v0
	v_mov_b32_e32 v110, v0
	v_mov_b32_e32 v111, v0
	v_mov_b32_e32 v120, v0
	v_mov_b32_e32 v121, v0
	v_mov_b32_e32 v122, v0
	v_mov_b32_e32 v123, v0
	v_mov_b32_e32 v124, v0
	v_mov_b32_e32 v125, v0
	v_mov_b32_e32 v126, v0
	v_mov_b32_e32 v127, v0
	v_xor_b32_e32 v150, 64, v146
	v_xor_b32_e32 v151, 64, v147
	v_xor_b32_e32 v216, 64, v148
	v_add_u32_e32 v217, 0x18000, v145
	v_xor_b32_e32 v220, 64, v217
	s_waitcnt vmcnt(0)
	s_cmpk_lt_u32 s3, 0x100
	s_cbranch_scc1 .Lst_in_s2
	s_barrier

.LBB0_362:
	s_ashr_i32 s31, s30, 31
	v_cmp_lt_i64_e32 vcc, s[10:11], v[176:177]
	s_lshl_b64 s[10:11], s[30:31], 20
	s_add_u32 s34, s80, s10
	s_addc_u32 s35, s81, s11
	s_and_b64 s[10:11], vcc, exec
	s_cselect_b32 s31, s35, s7
	s_cselect_b32 s33, s34, s6
	s_ashr_i32 s29, s28, 31
	s_lshl_b64 s[10:11], s[28:29], 19
	s_add_u32 s36, s40, s10
	s_addc_u32 s37, s41, s11
	s_and_b64 s[10:11], vcc, exec
	s_cselect_b32 s29, s37, s9
	s_cselect_b32 s62, s36, s8
	s_add_u32 s63, s8, 0x100
	v_mov_b32_e32 v0, 0
	s_addc_u32 s64, s9, 0
	s_mov_b32 s65, -2
	v_mov_b32_e32 v1, v0
	v_mov_b32_e32 v2, v0
	v_mov_b32_e32 v3, v0
	v_mov_b32_e32 v64, v0
	v_mov_b32_e32 v65, v0
	v_mov_b32_e32 v66, v0
	v_mov_b32_e32 v67, v0
	v_mov_b32_e32 v8, v0
	v_mov_b32_e32 v9, v0
	v_mov_b32_e32 v10, v0
	v_mov_b32_e32 v11, v0
	v_mov_b32_e32 v68, v0
	v_mov_b32_e32 v69, v0
	v_mov_b32_e32 v70, v0
	v_mov_b32_e32 v71, v0
	v_mov_b32_e32 v12, v0
	v_mov_b32_e32 v13, v0
	v_mov_b32_e32 v14, v0
	v_mov_b32_e32 v15, v0
	v_mov_b32_e32 v110, v0
	v_mov_b32_e32 v111, v0
	v_mov_b32_e32 v112, v0
	v_mov_b32_e32 v113, v0
	v_mov_b32_e32 v16, v0
	v_mov_b32_e32 v17, v0
	v_mov_b32_e32 v18, v0
	v_mov_b32_e32 v19, v0
	v_mov_b32_e32 v118, v0
	v_mov_b32_e32 v119, v0
	v_mov_b32_e32 v120, v0
	v_mov_b32_e32 v121, v0
	v_mov_b32_e32 v4, v0
	v_mov_b32_e32 v5, v0
	v_mov_b32_e32 v6, v0
	v_mov_b32_e32 v7, v0
	v_mov_b32_e32 v72, v0
	v_mov_b32_e32 v73, v0
	v_mov_b32_e32 v74, v0
	v_mov_b32_e32 v75, v0
	v_mov_b32_e32 v20, v0
	v_mov_b32_e32 v21, v0
	v_mov_b32_e32 v22, v0
	v_mov_b32_e32 v23, v0
	v_mov_b32_e32 v114, v0
	v_mov_b32_e32 v115, v0
	v_mov_b32_e32 v116, v0
	v_mov_b32_e32 v117, v0
	v_mov_b32_e32 v24, v0
	v_mov_b32_e32 v25, v0
	v_mov_b32_e32 v26, v0
	v_mov_b32_e32 v27, v0
	v_mov_b32_e32 v122, v0
	v_mov_b32_e32 v123, v0
	v_mov_b32_e32 v124, v0
	v_mov_b32_e32 v125, v0
	v_mov_b32_e32 v28, v0
	v_mov_b32_e32 v29, v0
	v_mov_b32_e32 v30, v0
	v_mov_b32_e32 v31, v0
	v_mov_b32_e32 v126, v0
	v_mov_b32_e32 v127, v0
	v_mov_b32_e32 v128, v0
	v_mov_b32_e32 v129, v0
	v_mov_b32_e32 v32, v0
	v_mov_b32_e32 v33, v0
	v_mov_b32_e32 v34, v0
	v_mov_b32_e32 v35, v0
	v_mov_b32_e32 v130, v0
	v_mov_b32_e32 v131, v0
	v_mov_b32_e32 v132, v0
	v_mov_b32_e32 v133, v0
	v_mov_b32_e32 v36, v0
	v_mov_b32_e32 v37, v0
	v_mov_b32_e32 v38, v0
	v_mov_b32_e32 v39, v0
	v_mov_b32_e32 v134, v0
	v_mov_b32_e32 v135, v0
	v_mov_b32_e32 v136, v0
	v_mov_b32_e32 v137, v0
	v_mov_b32_e32 v44, v0
	v_mov_b32_e32 v45, v0
	v_mov_b32_e32 v46, v0
	v_mov_b32_e32 v47, v0
	v_mov_b32_e32 v142, v0
	v_mov_b32_e32 v143, v0
	v_mov_b32_e32 v144, v0
	v_mov_b32_e32 v145, v0
	v_mov_b32_e32 v56, v0
	v_mov_b32_e32 v57, v0
	v_mov_b32_e32 v58, v0
	v_mov_b32_e32 v59, v0
	v_mov_b32_e32 v154, v0
	v_mov_b32_e32 v155, v0
	v_mov_b32_e32 v156, v0
	v_mov_b32_e32 v157, v0
	v_mov_b32_e32 v40, v0
	v_mov_b32_e32 v41, v0
	v_mov_b32_e32 v42, v0
	v_mov_b32_e32 v43, v0
	v_mov_b32_e32 v138, v0
	v_mov_b32_e32 v139, v0
	v_mov_b32_e32 v140, v0
	v_mov_b32_e32 v141, v0
	v_mov_b32_e32 v48, v0
	v_mov_b32_e32 v49, v0
	v_mov_b32_e32 v50, v0
	v_mov_b32_e32 v51, v0
	v_mov_b32_e32 v146, v0
	v_mov_b32_e32 v147, v0
	v_mov_b32_e32 v148, v0
	v_mov_b32_e32 v149, v0
	v_mov_b32_e32 v52, v0
	v_mov_b32_e32 v53, v0
	v_mov_b32_e32 v54, v0
	v_mov_b32_e32 v55, v0
	v_mov_b32_e32 v150, v0
	v_mov_b32_e32 v151, v0
	v_mov_b32_e32 v152, v0
	v_mov_b32_e32 v153, v0
	v_mov_b32_e32 v60, v0
	v_mov_b32_e32 v61, v0
	v_mov_b32_e32 v62, v0
	v_mov_b32_e32 v63, v0
	v_mov_b32_e32 v158, v0
	v_mov_b32_e32 v159, v0
	v_mov_b32_e32 v160, v0
	v_mov_b32_e32 v161, v0
	v_xor_b32_e32 v216, 64, v231
	v_xor_b32_e32 v217, 64, v241
	v_xor_b32_e32 v244, 64, v242
	v_add_u32_e32 v245, 0x18000, v229
	v_xor_b32_e32 v246, 64, v245
	v_add_u32_e32 v247, 0x1c000, v229
	v_xor_b32_e32 v248, 64, v247
	s_waitcnt vmcnt(0)
	s_cmpk_lt_u32 s3, 0x100
	s_cbranch_scc1 .Lst_in_s3
	s_barrier

.LBB0_507:
	s_add_u32 s0, s0, 0x160080
	s_addc_u32 s1, s1, 0
	s_add_u32 s39, s16, 0x100
	v_mov_b32_e32 v0, 0
	s_addc_u32 s40, s17, 0
	s_mov_b32 s41, -2
	s_waitcnt lgkmcnt(0)
	v_mov_b32_e32 v1, v0
	v_mov_b32_e32 v2, v0
	v_mov_b32_e32 v3, v0
	v_mov_b32_e32 v4, v0
	v_mov_b32_e32 v5, v0
	v_mov_b32_e32 v6, v0
	v_mov_b32_e32 v7, v0
	v_mov_b32_e32 v16, v0
	v_mov_b32_e32 v17, v0
	v_mov_b32_e32 v18, v0
	v_mov_b32_e32 v19, v0
	v_mov_b32_e32 v20, v0
	v_mov_b32_e32 v21, v0
	v_mov_b32_e32 v22, v0
	v_mov_b32_e32 v23, v0
	v_mov_b32_e32 v32, v0
	v_mov_b32_e32 v33, v0
	v_mov_b32_e32 v34, v0
	v_mov_b32_e32 v35, v0
	v_mov_b32_e32 v36, v0
	v_mov_b32_e32 v37, v0
	v_mov_b32_e32 v38, v0
	v_mov_b32_e32 v39, v0
	v_mov_b32_e32 v48, v0
	v_mov_b32_e32 v49, v0
	v_mov_b32_e32 v50, v0
	v_mov_b32_e32 v51, v0
	v_mov_b32_e32 v52, v0
	v_mov_b32_e32 v53, v0
	v_mov_b32_e32 v54, v0
	v_mov_b32_e32 v55, v0
	v_mov_b32_e32 v8, v0
	v_mov_b32_e32 v9, v0
	v_mov_b32_e32 v10, v0
	v_mov_b32_e32 v11, v0
	v_mov_b32_e32 v12, v0
	v_mov_b32_e32 v13, v0
	v_mov_b32_e32 v14, v0
	v_mov_b32_e32 v15, v0
	v_mov_b32_e32 v24, v0
	v_mov_b32_e32 v25, v0
	v_mov_b32_e32 v26, v0
	v_mov_b32_e32 v27, v0
	v_mov_b32_e32 v28, v0
	v_mov_b32_e32 v29, v0
	v_mov_b32_e32 v30, v0
	v_mov_b32_e32 v31, v0
	v_mov_b32_e32 v40, v0
	v_mov_b32_e32 v41, v0
	v_mov_b32_e32 v42, v0
	v_mov_b32_e32 v43, v0
	v_mov_b32_e32 v44, v0
	v_mov_b32_e32 v45, v0
	v_mov_b32_e32 v46, v0
	v_mov_b32_e32 v47, v0
	v_mov_b32_e32 v56, v0
	v_mov_b32_e32 v57, v0
	v_mov_b32_e32 v58, v0
	v_mov_b32_e32 v59, v0
	v_mov_b32_e32 v60, v0
	v_mov_b32_e32 v61, v0
	v_mov_b32_e32 v62, v0
	v_mov_b32_e32 v63, v0
	v_mov_b32_e32 v64, v0
	v_mov_b32_e32 v65, v0
	v_mov_b32_e32 v66, v0
	v_mov_b32_e32 v67, v0
	v_mov_b32_e32 v68, v0
	v_mov_b32_e32 v69, v0
	v_mov_b32_e32 v70, v0
	v_mov_b32_e32 v71, v0
	v_mov_b32_e32 v80, v0
	v_mov_b32_e32 v81, v0
	v_mov_b32_e32 v82, v0
	v_mov_b32_e32 v83, v0
	v_mov_b32_e32 v84, v0
	v_mov_b32_e32 v85, v0
	v_mov_b32_e32 v86, v0
	v_mov_b32_e32 v87, v0
	v_mov_b32_e32 v96, v0
	v_mov_b32_e32 v97, v0
	v_mov_b32_e32 v98, v0
	v_mov_b32_e32 v99, v0
	v_mov_b32_e32 v100, v0
	v_mov_b32_e32 v101, v0
	v_mov_b32_e32 v102, v0
	v_mov_b32_e32 v103, v0
	v_mov_b32_e32 v112, v0
	v_mov_b32_e32 v113, v0
	v_mov_b32_e32 v114, v0
	v_mov_b32_e32 v115, v0
	v_mov_b32_e32 v116, v0
	v_mov_b32_e32 v117, v0
	v_mov_b32_e32 v118, v0
	v_mov_b32_e32 v119, v0
	v_mov_b32_e32 v72, v0
	v_mov_b32_e32 v73, v0
	v_mov_b32_e32 v74, v0
	v_mov_b32_e32 v75, v0
	v_mov_b32_e32 v76, v0
	v_mov_b32_e32 v77, v0
	v_mov_b32_e32 v78, v0
	v_mov_b32_e32 v79, v0
	v_mov_b32_e32 v88, v0
	v_mov_b32_e32 v89, v0
	v_mov_b32_e32 v90, v0
	v_mov_b32_e32 v91, v0
	v_mov_b32_e32 v92, v0
	v_mov_b32_e32 v93, v0
	v_mov_b32_e32 v94, v0
	v_mov_b32_e32 v95, v0
	v_mov_b32_e32 v104, v0
	v_mov_b32_e32 v105, v0
	v_mov_b32_e32 v106, v0
	v_mov_b32_e32 v107, v0
	v_mov_b32_e32 v108, v0
	v_mov_b32_e32 v109, v0
	v_mov_b32_e32 v110, v0
	v_mov_b32_e32 v111, v0
	v_mov_b32_e32 v120, v0
	v_mov_b32_e32 v121, v0
	v_mov_b32_e32 v122, v0
	v_mov_b32_e32 v123, v0
	v_mov_b32_e32 v124, v0
	v_mov_b32_e32 v125, v0
	v_mov_b32_e32 v126, v0
	v_mov_b32_e32 v127, v0
	v_xor_b32_e32 v216, 64, v141
	v_xor_b32_e32 v217, 64, v142
	v_xor_b32_e32 v244, 64, v143
	v_add_u32_e32 v245, 0x18000, v140
	v_xor_b32_e32 v246, 64, v245
	s_waitcnt vmcnt(0)
	s_cmpk_lt_u32 s3, 0x100
	s_cbranch_scc1 .Lst_in_s4
	s_barrier

.LBB0_598:
	s_ashr_i32 s21, s20, 31
	v_cmp_lt_i64_e32 vcc, s[22:23], v[136:137]
	s_lshl_b64 s[22:23], s[20:21], 20
	s_add_u32 s22, s80, s22
	s_addc_u32 s23, s81, s23
	s_and_b64 s[24:25], vcc, exec
	s_cselect_b32 s1, s23, s27
	s_cselect_b32 s13, s22, s26
	s_ashr_i32 s19, s18, 31
	s_lshl_b64 s[24:25], s[18:19], 20
	s_add_u32 s24, s34, s24
	s_addc_u32 s25, s35, s25
	s_and_b64 s[30:31], vcc, exec
	s_cselect_b32 s19, s25, s29
	s_cselect_b32 s21, s24, s28
	s_add_u32 s26, s26, 0x80080
	s_addc_u32 s27, s27, 0
	s_add_u32 s33, s28, 0x100
	v_mov_b32_e32 v0, 0
	s_addc_u32 s48, s29, 0
	s_mov_b32 s49, -2
	s_waitcnt lgkmcnt(0)
	v_mov_b32_e32 v1, v0
	v_mov_b32_e32 v2, v0
	v_mov_b32_e32 v3, v0
	v_mov_b32_e32 v4, v0
	v_mov_b32_e32 v5, v0
	v_mov_b32_e32 v6, v0
	v_mov_b32_e32 v7, v0
	v_mov_b32_e32 v16, v0
	v_mov_b32_e32 v17, v0
	v_mov_b32_e32 v18, v0
	v_mov_b32_e32 v19, v0
	v_mov_b32_e32 v20, v0
	v_mov_b32_e32 v21, v0
	v_mov_b32_e32 v22, v0
	v_mov_b32_e32 v23, v0
	v_mov_b32_e32 v32, v0
	v_mov_b32_e32 v33, v0
	v_mov_b32_e32 v34, v0
	v_mov_b32_e32 v35, v0
	v_mov_b32_e32 v36, v0
	v_mov_b32_e32 v37, v0
	v_mov_b32_e32 v38, v0
	v_mov_b32_e32 v39, v0
	v_mov_b32_e32 v48, v0
	v_mov_b32_e32 v49, v0
	v_mov_b32_e32 v50, v0
	v_mov_b32_e32 v51, v0
	v_mov_b32_e32 v52, v0
	v_mov_b32_e32 v53, v0
	v_mov_b32_e32 v54, v0
	v_mov_b32_e32 v55, v0
	v_mov_b32_e32 v8, v0
	v_mov_b32_e32 v9, v0
	v_mov_b32_e32 v10, v0
	v_mov_b32_e32 v11, v0
	v_mov_b32_e32 v12, v0
	v_mov_b32_e32 v13, v0
	v_mov_b32_e32 v14, v0
	v_mov_b32_e32 v15, v0
	v_mov_b32_e32 v24, v0
	v_mov_b32_e32 v25, v0
	v_mov_b32_e32 v26, v0
	v_mov_b32_e32 v27, v0
	v_mov_b32_e32 v28, v0
	v_mov_b32_e32 v29, v0
	v_mov_b32_e32 v30, v0
	v_mov_b32_e32 v31, v0
	v_mov_b32_e32 v40, v0
	v_mov_b32_e32 v41, v0
	v_mov_b32_e32 v42, v0
	v_mov_b32_e32 v43, v0
	v_mov_b32_e32 v44, v0
	v_mov_b32_e32 v45, v0
	v_mov_b32_e32 v46, v0
	v_mov_b32_e32 v47, v0
	v_mov_b32_e32 v56, v0
	v_mov_b32_e32 v57, v0
	v_mov_b32_e32 v58, v0
	v_mov_b32_e32 v59, v0
	v_mov_b32_e32 v60, v0
	v_mov_b32_e32 v61, v0
	v_mov_b32_e32 v62, v0
	v_mov_b32_e32 v63, v0
	v_mov_b32_e32 v64, v0
	v_mov_b32_e32 v65, v0
	v_mov_b32_e32 v66, v0
	v_mov_b32_e32 v67, v0
	v_mov_b32_e32 v68, v0
	v_mov_b32_e32 v69, v0
	v_mov_b32_e32 v70, v0
	v_mov_b32_e32 v71, v0
	v_mov_b32_e32 v80, v0
	v_mov_b32_e32 v81, v0
	v_mov_b32_e32 v82, v0
	v_mov_b32_e32 v83, v0
	v_mov_b32_e32 v84, v0
	v_mov_b32_e32 v85, v0
	v_mov_b32_e32 v86, v0
	v_mov_b32_e32 v87, v0
	v_mov_b32_e32 v96, v0
	v_mov_b32_e32 v97, v0
	v_mov_b32_e32 v98, v0
	v_mov_b32_e32 v99, v0
	v_mov_b32_e32 v100, v0
	v_mov_b32_e32 v101, v0
	v_mov_b32_e32 v102, v0
	v_mov_b32_e32 v103, v0
	v_mov_b32_e32 v112, v0
	v_mov_b32_e32 v113, v0
	v_mov_b32_e32 v114, v0
	v_mov_b32_e32 v115, v0
	v_mov_b32_e32 v116, v0
	v_mov_b32_e32 v117, v0
	v_mov_b32_e32 v118, v0
	v_mov_b32_e32 v119, v0
	v_mov_b32_e32 v72, v0
	v_mov_b32_e32 v73, v0
	v_mov_b32_e32 v74, v0
	v_mov_b32_e32 v75, v0
	v_mov_b32_e32 v76, v0
	v_mov_b32_e32 v77, v0
	v_mov_b32_e32 v78, v0
	v_mov_b32_e32 v79, v0
	v_mov_b32_e32 v88, v0
	v_mov_b32_e32 v89, v0
	v_mov_b32_e32 v90, v0
	v_mov_b32_e32 v91, v0
	v_mov_b32_e32 v92, v0
	v_mov_b32_e32 v93, v0
	v_mov_b32_e32 v94, v0
	v_mov_b32_e32 v95, v0
	v_mov_b32_e32 v104, v0
	v_mov_b32_e32 v105, v0
	v_mov_b32_e32 v106, v0
	v_mov_b32_e32 v107, v0
	v_mov_b32_e32 v108, v0
	v_mov_b32_e32 v109, v0
	v_mov_b32_e32 v110, v0
	v_mov_b32_e32 v111, v0
	v_mov_b32_e32 v120, v0
	v_mov_b32_e32 v121, v0
	v_mov_b32_e32 v122, v0
	v_mov_b32_e32 v123, v0
	v_mov_b32_e32 v124, v0
	v_mov_b32_e32 v125, v0
	v_mov_b32_e32 v126, v0
	v_mov_b32_e32 v127, v0
	v_xor_b32_e32 v144, 64, v149
	v_xor_b32_e32 v145, 64, v150
	v_xor_b32_e32 v216, 64, v151
	v_add_u32_e32 v217, 0x18000, v147
	v_xor_b32_e32 v234, 64, v217
	v_add_u32_e32 v235, 0x1c000, v147
	v_xor_b32_e32 v252, 64, v235
	s_waitcnt vmcnt(0)
	s_cmpk_lt_u32 s3, 0x100
	s_cbranch_scc1 .Lst_in_s5
	s_barrier

.LBB0_759:
	s_ashr_i32 s15, s14, 31
	v_cmp_lt_i64_e32 vcc, s[16:17], v[136:137]
	s_lshl_b64 s[16:17], s[14:15], 21
	s_add_u32 s16, s96, s16
	s_addc_u32 s17, s97, s17
	s_and_b64 s[18:19], vcc, exec
	s_cselect_b32 s1, s17, s21
	s_cselect_b32 s9, s16, s20
	s_ashr_i32 s13, s12, 31
	s_lshl_b64 s[18:19], s[12:13], 20
	s_add_u32 s18, s26, s18
	s_addc_u32 s19, s27, s19
	s_and_b64 s[24:25], vcc, exec
	s_cselect_b32 s13, s19, s23
	s_cselect_b32 s15, s18, s22
	s_add_u32 s20, s20, 0x100080
	s_addc_u32 s21, s21, 0
	s_add_u32 s43, s22, 0x100
	v_mov_b32_e32 v0, 0
	s_addc_u32 s44, s23, 0
	s_mov_b32 s45, -2
	s_waitcnt lgkmcnt(0)
	v_mov_b32_e32 v1, v0
	v_mov_b32_e32 v2, v0
	v_mov_b32_e32 v3, v0
	v_mov_b32_e32 v4, v0
	v_mov_b32_e32 v5, v0
	v_mov_b32_e32 v6, v0
	v_mov_b32_e32 v7, v0
	v_mov_b32_e32 v16, v0
	v_mov_b32_e32 v17, v0
	v_mov_b32_e32 v18, v0
	v_mov_b32_e32 v19, v0
	v_mov_b32_e32 v20, v0
	v_mov_b32_e32 v21, v0
	v_mov_b32_e32 v22, v0
	v_mov_b32_e32 v23, v0
	v_mov_b32_e32 v32, v0
	v_mov_b32_e32 v33, v0
	v_mov_b32_e32 v34, v0
	v_mov_b32_e32 v35, v0
	v_mov_b32_e32 v36, v0
	v_mov_b32_e32 v37, v0
	v_mov_b32_e32 v38, v0
	v_mov_b32_e32 v39, v0
	v_mov_b32_e32 v48, v0
	v_mov_b32_e32 v49, v0
	v_mov_b32_e32 v50, v0
	v_mov_b32_e32 v51, v0
	v_mov_b32_e32 v52, v0
	v_mov_b32_e32 v53, v0
	v_mov_b32_e32 v54, v0
	v_mov_b32_e32 v55, v0
	v_mov_b32_e32 v8, v0
	v_mov_b32_e32 v9, v0
	v_mov_b32_e32 v10, v0
	v_mov_b32_e32 v11, v0
	v_mov_b32_e32 v12, v0
	v_mov_b32_e32 v13, v0
	v_mov_b32_e32 v14, v0
	v_mov_b32_e32 v15, v0
	v_mov_b32_e32 v24, v0
	v_mov_b32_e32 v25, v0
	v_mov_b32_e32 v26, v0
	v_mov_b32_e32 v27, v0
	v_mov_b32_e32 v28, v0
	v_mov_b32_e32 v29, v0
	v_mov_b32_e32 v30, v0
	v_mov_b32_e32 v31, v0
	v_mov_b32_e32 v40, v0
	v_mov_b32_e32 v41, v0
	v_mov_b32_e32 v42, v0
	v_mov_b32_e32 v43, v0
	v_mov_b32_e32 v44, v0
	v_mov_b32_e32 v45, v0
	v_mov_b32_e32 v46, v0
	v_mov_b32_e32 v47, v0
	v_mov_b32_e32 v56, v0
	v_mov_b32_e32 v57, v0
	v_mov_b32_e32 v58, v0
	v_mov_b32_e32 v59, v0
	v_mov_b32_e32 v60, v0
	v_mov_b32_e32 v61, v0
	v_mov_b32_e32 v62, v0
	v_mov_b32_e32 v63, v0
	v_mov_b32_e32 v64, v0
	v_mov_b32_e32 v65, v0
	v_mov_b32_e32 v66, v0
	v_mov_b32_e32 v67, v0
	v_mov_b32_e32 v68, v0
	v_mov_b32_e32 v69, v0
	v_mov_b32_e32 v70, v0
	v_mov_b32_e32 v71, v0
	v_mov_b32_e32 v80, v0
	v_mov_b32_e32 v81, v0
	v_mov_b32_e32 v82, v0
	v_mov_b32_e32 v83, v0
	v_mov_b32_e32 v84, v0
	v_mov_b32_e32 v85, v0
	v_mov_b32_e32 v86, v0
	v_mov_b32_e32 v87, v0
	v_mov_b32_e32 v96, v0
	v_mov_b32_e32 v97, v0
	v_mov_b32_e32 v98, v0
	v_mov_b32_e32 v99, v0
	v_mov_b32_e32 v100, v0
	v_mov_b32_e32 v101, v0
	v_mov_b32_e32 v102, v0
	v_mov_b32_e32 v103, v0
	v_mov_b32_e32 v112, v0
	v_mov_b32_e32 v113, v0
	v_mov_b32_e32 v114, v0
	v_mov_b32_e32 v115, v0
	v_mov_b32_e32 v116, v0
	v_mov_b32_e32 v117, v0
	v_mov_b32_e32 v118, v0
	v_mov_b32_e32 v119, v0
	v_mov_b32_e32 v72, v0
	v_mov_b32_e32 v73, v0
	v_mov_b32_e32 v74, v0
	v_mov_b32_e32 v75, v0
	v_mov_b32_e32 v76, v0
	v_mov_b32_e32 v77, v0
	v_mov_b32_e32 v78, v0
	v_mov_b32_e32 v79, v0
	v_mov_b32_e32 v88, v0
	v_mov_b32_e32 v89, v0
	v_mov_b32_e32 v90, v0
	v_mov_b32_e32 v91, v0
	v_mov_b32_e32 v92, v0
	v_mov_b32_e32 v93, v0
	v_mov_b32_e32 v94, v0
	v_mov_b32_e32 v95, v0
	v_mov_b32_e32 v104, v0
	v_mov_b32_e32 v105, v0
	v_mov_b32_e32 v106, v0
	v_mov_b32_e32 v107, v0
	v_mov_b32_e32 v108, v0
	v_mov_b32_e32 v109, v0
	v_mov_b32_e32 v110, v0
	v_mov_b32_e32 v111, v0
	v_mov_b32_e32 v120, v0
	v_mov_b32_e32 v121, v0
	v_mov_b32_e32 v122, v0
	v_mov_b32_e32 v123, v0
	v_mov_b32_e32 v124, v0
	v_mov_b32_e32 v125, v0
	v_mov_b32_e32 v126, v0
	v_mov_b32_e32 v127, v0
	v_xor_b32_e32 v216, 64, v145
	v_xor_b32_e32 v217, 64, v146
	v_xor_b32_e32 v234, 64, v147
	v_add_u32_e32 v235, 0x18000, v144
	v_xor_b32_e32 v244, 64, v235
	s_waitcnt vmcnt(0)
	s_cmpk_lt_u32 s3, 0x100
	s_cbranch_scc1 .Lst_in_s7
	s_barrier

.LBB0_839:
	s_ashr_i32 s37, s36, 31
	v_cmp_lt_i64_e32 vcc, s[12:13], v[184:185]
	s_lshl_b64 s[12:13], s[36:37], 20
	s_add_u32 s38, s80, s12
	s_addc_u32 s39, s81, s13
	s_and_b64 s[12:13], vcc, exec
	s_cselect_b32 s33, s39, s9
	s_cselect_b32 s37, s38, s8
	s_ashr_i32 s35, s34, 31
	s_lshl_b64 s[12:13], s[34:35], 19
	s_add_u32 s40, s44, s12
	s_addc_u32 s41, s45, s13
	s_and_b64 s[12:13], vcc, exec
	s_cselect_b32 s35, s41, s11
	s_cselect_b32 s64, s40, s10
	s_add_u32 s65, s10, 0x100
	v_mov_b32_e32 v0, 0
	s_addc_u32 s66, s11, 0
	s_mov_b32 s67, -2
	v_mov_b32_e32 v1, v0
	v_mov_b32_e32 v2, v0
	v_mov_b32_e32 v3, v0
	v_mov_b32_e32 v64, v0
	v_mov_b32_e32 v65, v0
	v_mov_b32_e32 v66, v0
	v_mov_b32_e32 v67, v0
	v_mov_b32_e32 v8, v0
	v_mov_b32_e32 v9, v0
	v_mov_b32_e32 v10, v0
	v_mov_b32_e32 v11, v0
	v_mov_b32_e32 v68, v0
	v_mov_b32_e32 v69, v0
	v_mov_b32_e32 v70, v0
	v_mov_b32_e32 v71, v0
	v_mov_b32_e32 v12, v0
	v_mov_b32_e32 v13, v0
	v_mov_b32_e32 v14, v0
	v_mov_b32_e32 v15, v0
	v_mov_b32_e32 v110, v0
	v_mov_b32_e32 v111, v0
	v_mov_b32_e32 v112, v0
	v_mov_b32_e32 v113, v0
	v_mov_b32_e32 v16, v0
	v_mov_b32_e32 v17, v0
	v_mov_b32_e32 v18, v0
	v_mov_b32_e32 v19, v0
	v_mov_b32_e32 v118, v0
	v_mov_b32_e32 v119, v0
	v_mov_b32_e32 v120, v0
	v_mov_b32_e32 v121, v0
	v_mov_b32_e32 v4, v0
	v_mov_b32_e32 v5, v0
	v_mov_b32_e32 v6, v0
	v_mov_b32_e32 v7, v0
	v_mov_b32_e32 v72, v0
	v_mov_b32_e32 v73, v0
	v_mov_b32_e32 v74, v0
	v_mov_b32_e32 v75, v0
	v_mov_b32_e32 v20, v0
	v_mov_b32_e32 v21, v0
	v_mov_b32_e32 v22, v0
	v_mov_b32_e32 v23, v0
	v_mov_b32_e32 v114, v0
	v_mov_b32_e32 v115, v0
	v_mov_b32_e32 v116, v0
	v_mov_b32_e32 v117, v0
	v_mov_b32_e32 v24, v0
	v_mov_b32_e32 v25, v0
	v_mov_b32_e32 v26, v0
	v_mov_b32_e32 v27, v0
	v_mov_b32_e32 v122, v0
	v_mov_b32_e32 v123, v0
	v_mov_b32_e32 v124, v0
	v_mov_b32_e32 v125, v0
	v_mov_b32_e32 v28, v0
	v_mov_b32_e32 v29, v0
	v_mov_b32_e32 v30, v0
	v_mov_b32_e32 v31, v0
	v_mov_b32_e32 v126, v0
	v_mov_b32_e32 v127, v0
	v_mov_b32_e32 v128, v0
	v_mov_b32_e32 v129, v0
	v_mov_b32_e32 v32, v0
	v_mov_b32_e32 v33, v0
	v_mov_b32_e32 v34, v0
	v_mov_b32_e32 v35, v0
	v_mov_b32_e32 v130, v0
	v_mov_b32_e32 v131, v0
	v_mov_b32_e32 v132, v0
	v_mov_b32_e32 v133, v0
	v_mov_b32_e32 v36, v0
	v_mov_b32_e32 v37, v0
	v_mov_b32_e32 v38, v0
	v_mov_b32_e32 v39, v0
	v_mov_b32_e32 v134, v0
	v_mov_b32_e32 v135, v0
	v_mov_b32_e32 v136, v0
	v_mov_b32_e32 v137, v0
	v_mov_b32_e32 v44, v0
	v_mov_b32_e32 v45, v0
	v_mov_b32_e32 v46, v0
	v_mov_b32_e32 v47, v0
	v_mov_b32_e32 v142, v0
	v_mov_b32_e32 v143, v0
	v_mov_b32_e32 v144, v0
	v_mov_b32_e32 v145, v0
	v_mov_b32_e32 v56, v0
	v_mov_b32_e32 v57, v0
	v_mov_b32_e32 v58, v0
	v_mov_b32_e32 v59, v0
	v_mov_b32_e32 v154, v0
	v_mov_b32_e32 v155, v0
	v_mov_b32_e32 v156, v0
	v_mov_b32_e32 v157, v0
	v_mov_b32_e32 v40, v0
	v_mov_b32_e32 v41, v0
	v_mov_b32_e32 v42, v0
	v_mov_b32_e32 v43, v0
	v_mov_b32_e32 v138, v0
	v_mov_b32_e32 v139, v0
	v_mov_b32_e32 v140, v0
	v_mov_b32_e32 v141, v0
	v_mov_b32_e32 v48, v0
	v_mov_b32_e32 v49, v0
	v_mov_b32_e32 v50, v0
	v_mov_b32_e32 v51, v0
	v_mov_b32_e32 v146, v0
	v_mov_b32_e32 v147, v0
	v_mov_b32_e32 v148, v0
	v_mov_b32_e32 v149, v0
	v_mov_b32_e32 v52, v0
	v_mov_b32_e32 v53, v0
	v_mov_b32_e32 v54, v0
	v_mov_b32_e32 v55, v0
	v_mov_b32_e32 v150, v0
	v_mov_b32_e32 v151, v0
	v_mov_b32_e32 v152, v0
	v_mov_b32_e32 v153, v0
	v_mov_b32_e32 v60, v0
	v_mov_b32_e32 v61, v0
	v_mov_b32_e32 v62, v0
	v_mov_b32_e32 v63, v0
	v_mov_b32_e32 v158, v0
	v_mov_b32_e32 v159, v0
	v_mov_b32_e32 v160, v0
	v_mov_b32_e32 v161, v0
	v_xor_b32_e32 v220, 64, v171
	v_xor_b32_e32 v221, 64, v173
	v_xor_b32_e32 v238, 64, v175
	v_add_u32_e32 v239, 0x18000, v169
	v_xor_b32_e32 v240, 64, v239
	v_add_u32_e32 v241, 0x1c000, v169
	v_xor_b32_e32 v242, 64, v241
	s_waitcnt vmcnt(0)
	s_cmpk_lt_u32 s3, 0x100
	s_cbranch_scc1 .Lst_in_s8
	s_barrier

.LBB0_984:
	s_add_u32 s0, s0, 0x160080
	s_addc_u32 s1, s1, 0
	s_add_u32 s39, s14, 0x100
	v_mov_b32_e32 v0, 0
	s_addc_u32 s40, s15, 0
	s_mov_b32 s41, -2
	s_waitcnt lgkmcnt(0)
	v_mov_b32_e32 v1, v0
	v_mov_b32_e32 v2, v0
	v_mov_b32_e32 v3, v0
	v_mov_b32_e32 v4, v0
	v_mov_b32_e32 v5, v0
	v_mov_b32_e32 v6, v0
	v_mov_b32_e32 v7, v0
	v_mov_b32_e32 v16, v0
	v_mov_b32_e32 v17, v0
	v_mov_b32_e32 v18, v0
	v_mov_b32_e32 v19, v0
	v_mov_b32_e32 v20, v0
	v_mov_b32_e32 v21, v0
	v_mov_b32_e32 v22, v0
	v_mov_b32_e32 v23, v0
	v_mov_b32_e32 v32, v0
	v_mov_b32_e32 v33, v0
	v_mov_b32_e32 v34, v0
	v_mov_b32_e32 v35, v0
	v_mov_b32_e32 v36, v0
	v_mov_b32_e32 v37, v0
	v_mov_b32_e32 v38, v0
	v_mov_b32_e32 v39, v0
	v_mov_b32_e32 v48, v0
	v_mov_b32_e32 v49, v0
	v_mov_b32_e32 v50, v0
	v_mov_b32_e32 v51, v0
	v_mov_b32_e32 v52, v0
	v_mov_b32_e32 v53, v0
	v_mov_b32_e32 v54, v0
	v_mov_b32_e32 v55, v0
	v_mov_b32_e32 v8, v0
	v_mov_b32_e32 v9, v0
	v_mov_b32_e32 v10, v0
	v_mov_b32_e32 v11, v0
	v_mov_b32_e32 v12, v0
	v_mov_b32_e32 v13, v0
	v_mov_b32_e32 v14, v0
	v_mov_b32_e32 v15, v0
	v_mov_b32_e32 v24, v0
	v_mov_b32_e32 v25, v0
	v_mov_b32_e32 v26, v0
	v_mov_b32_e32 v27, v0
	v_mov_b32_e32 v28, v0
	v_mov_b32_e32 v29, v0
	v_mov_b32_e32 v30, v0
	v_mov_b32_e32 v31, v0
	v_mov_b32_e32 v40, v0
	v_mov_b32_e32 v41, v0
	v_mov_b32_e32 v42, v0
	v_mov_b32_e32 v43, v0
	v_mov_b32_e32 v44, v0
	v_mov_b32_e32 v45, v0
	v_mov_b32_e32 v46, v0
	v_mov_b32_e32 v47, v0
	v_mov_b32_e32 v56, v0
	v_mov_b32_e32 v57, v0
	v_mov_b32_e32 v58, v0
	v_mov_b32_e32 v59, v0
	v_mov_b32_e32 v60, v0
	v_mov_b32_e32 v61, v0
	v_mov_b32_e32 v62, v0
	v_mov_b32_e32 v63, v0
	v_mov_b32_e32 v64, v0
	v_mov_b32_e32 v65, v0
	v_mov_b32_e32 v66, v0
	v_mov_b32_e32 v67, v0
	v_mov_b32_e32 v68, v0
	v_mov_b32_e32 v69, v0
	v_mov_b32_e32 v70, v0
	v_mov_b32_e32 v71, v0
	v_mov_b32_e32 v80, v0
	v_mov_b32_e32 v81, v0
	v_mov_b32_e32 v82, v0
	v_mov_b32_e32 v83, v0
	v_mov_b32_e32 v84, v0
	v_mov_b32_e32 v85, v0
	v_mov_b32_e32 v86, v0
	v_mov_b32_e32 v87, v0
	v_mov_b32_e32 v96, v0
	v_mov_b32_e32 v97, v0
	v_mov_b32_e32 v98, v0
	v_mov_b32_e32 v99, v0
	v_mov_b32_e32 v100, v0
	v_mov_b32_e32 v101, v0
	v_mov_b32_e32 v102, v0
	v_mov_b32_e32 v103, v0
	v_mov_b32_e32 v112, v0
	v_mov_b32_e32 v113, v0
	v_mov_b32_e32 v114, v0
	v_mov_b32_e32 v115, v0
	v_mov_b32_e32 v116, v0
	v_mov_b32_e32 v117, v0
	v_mov_b32_e32 v118, v0
	v_mov_b32_e32 v119, v0
	v_mov_b32_e32 v72, v0
	v_mov_b32_e32 v73, v0
	v_mov_b32_e32 v74, v0
	v_mov_b32_e32 v75, v0
	v_mov_b32_e32 v76, v0
	v_mov_b32_e32 v77, v0
	v_mov_b32_e32 v78, v0
	v_mov_b32_e32 v79, v0
	v_mov_b32_e32 v88, v0
	v_mov_b32_e32 v89, v0
	v_mov_b32_e32 v90, v0
	v_mov_b32_e32 v91, v0
	v_mov_b32_e32 v92, v0
	v_mov_b32_e32 v93, v0
	v_mov_b32_e32 v94, v0
	v_mov_b32_e32 v95, v0
	v_mov_b32_e32 v104, v0
	v_mov_b32_e32 v105, v0
	v_mov_b32_e32 v106, v0
	v_mov_b32_e32 v107, v0
	v_mov_b32_e32 v108, v0
	v_mov_b32_e32 v109, v0
	v_mov_b32_e32 v110, v0
	v_mov_b32_e32 v111, v0
	v_mov_b32_e32 v120, v0
	v_mov_b32_e32 v121, v0
	v_mov_b32_e32 v122, v0
	v_mov_b32_e32 v123, v0
	v_mov_b32_e32 v124, v0
	v_mov_b32_e32 v125, v0
	v_mov_b32_e32 v126, v0
	v_mov_b32_e32 v127, v0
	v_xor_b32_e32 v216, 64, v141
	v_xor_b32_e32 v217, 64, v142
	v_xor_b32_e32 v218, 64, v143
	v_add_u32_e32 v219, 0x18000, v140
	v_xor_b32_e32 v220, 64, v219
	s_waitcnt vmcnt(0)
	s_cmpk_lt_u32 s3, 0x100
	s_cbranch_scc1 .Lst_in_s9
	s_barrier
